# v25 + diff-attn unit epilogue: 15 serialized sub-LN gain loads (each with vmcnt(0)) preloaded in one batch
# baseline (speedup 1.0000x reference)
.LBB0_122:
	s_cmpk_gt_u32 s1, 0xff
	s_waitcnt lgkmcnt(0)
	s_barrier
	s_cbranch_scc1 .LBB0_101
	ds_read_b128 v[74:77], v0
	ds_read_b128 v[80:83], v0 offset:4096
	ds_read_b128 v[92:95], v0 offset:8192
	s_waitcnt vmcnt(5)
	ds_read_b128 v[96:99], v0 offset:12288
	s_waitcnt vmcnt(4)
	ds_read_b128 v[100:103], v0 offset:16384
	s_waitcnt vmcnt(3)
	ds_read_b128 v[104:107], v0 offset:20480
	s_waitcnt vmcnt(2)
	ds_read_b128 v[108:111], v0 offset:24576
	s_waitcnt vmcnt(1)
	ds_read_b128 v[112:115], v0 offset:28672
	s_waitcnt vmcnt(0)
	ds_read_b128 v[116:119], v0 offset:32768
	ds_read_b128 v[120:123], v0 offset:36864
	ds_read_b128 v[124:127], v0 offset:40960
	ds_read_b128 v[128:131], v0 offset:45056
	ds_read_b128 v[132:135], v0 offset:49152
	ds_read_b128 v[136:139], v0 offset:53248
	ds_read_b128 v[140:143], v0 offset:57344
	ds_read_b128 v[84:87], v0 offset:61440
	s_add_u32 s14, s16, s8
	s_addc_u32 s15, s17, s9
	s_waitcnt lgkmcnt(14)
	v_pk_mul_f32 v[74:75], v[150:151], v[74:75]
	s_lshl_b32 s80, s11, 1
	s_waitcnt lgkmcnt(0)
	v_pk_mul_f32 v[66:67], v[150:151], v[84:85]
	v_pk_mul_f32 v[76:77], v[150:151], v[76:77]
	v_pk_fma_f32 v[14:15], v[14:15], v[68:69], v[66:67] op_sel_hi:[1,0,1] neg_lo:[0,0,1] neg_hi:[0,0,1]
	v_pk_mul_f32 v[66:67], v[150:151], v[86:87]
	global_load_dwordx4 v[86:89], v152, s[14:15]
	global_load_dwordx4 v[158:161], v152, s[14:15] offset:32
	global_load_dwordx4 v[170:173], v152, s[14:15] offset:64
	global_load_dwordx4 v[174:177], v152, s[14:15] offset:96
	global_load_dwordx4 v[178:181], v152, s[14:15] offset:128
	global_load_dwordx4 v[182:185], v152, s[14:15] offset:160
	global_load_dwordx4 v[186:189], v152, s[14:15] offset:192
	global_load_dwordx4 v[190:193], v152, s[14:15] offset:224
	global_load_dwordx4 v[194:197], v152, s[14:15] offset:256
	global_load_dwordx4 v[198:201], v152, s[14:15] offset:288
	global_load_dwordx4 v[202:205], v152, s[14:15] offset:320
	global_load_dwordx4 v[206:209], v152, s[14:15] offset:352
	global_load_dwordx4 v[210:213], v152, s[14:15] offset:384
	global_load_dwordx4 v[214:217], v152, s[14:15] offset:416
	global_load_dwordx4 v[218:221], v152, s[14:15] offset:448
	global_load_dwordx4 v[222:225], v152, s[14:15] offset:480
	v_pk_fma_f32 v[16:17], v[16:17], v[68:69], v[66:67] op_sel_hi:[1,0,1] neg_lo:[0,0,1] neg_hi:[0,0,1]
	v_lshl_add_u32 v66, s0, 12, v168
	v_ashrrev_i32_e32 v67, 31, v66
	v_lshlrev_b64 v[66:67], 11, v[66:67]
	v_lshl_add_u64 v[66:67], s[64:65], 0, v[66:67]
	v_pk_fma_f32 v[34:35], v[34:35], v[68:69], v[74:75] op_sel_hi:[1,0,1] neg_lo:[0,0,1] neg_hi:[0,0,1]
	v_lshl_add_u64 v[66:67], v[66:67], 0, s[80:81]
	v_lshlrev_b32_e32 v0, 3, v167
	v_pk_fma_f32 v[36:37], v[36:37], v[68:69], v[76:77] op_sel_hi:[1,0,1] neg_lo:[0,0,1] neg_hi:[0,0,1]
	v_pk_mul_f32 v[146:147], v[34:35], v[34:35]
	v_lshl_add_u64 v[70:71], v[66:67], 0, v[0:1]
	v_pk_mul_f32 v[144:145], v[36:37], v[36:37]
	v_add_f32_e32 v0, v146, v147
	v_add_f32_e32 v0, v144, v0
	v_add_f32_e32 v0, v145, v0
	v_pk_mul_f32 v[72:73], v[14:15], v[14:15]
	v_pk_mul_f32 v[78:79], v[16:17], v[16:17]
	s_mov_b64 s[0:1], 0xd880400
	v_lshl_add_u64 v[66:67], v[70:71], 0, s[0:1]
	s_mov_b32 s0, 0xd880000
	s_waitcnt vmcnt(0)
	v_pk_mul_f32 v[86:87], v[34:35], v[86:87]
	v_pk_mul_f32 v[34:35], v[150:151], v[82:83]
	v_pk_mul_f32 v[88:89], v[36:37], v[88:89]
	v_pk_fma_f32 v[82:83], v[40:41], v[68:69], v[34:35] op_sel_hi:[1,0,1] neg_lo:[0,0,1] neg_hi:[0,0,1]
	v_pk_mul_f32 v[34:35], v[150:151], v[80:81]
	v_pk_mul_f32 v[148:149], v[82:83], v[82:83]
	v_pk_fma_f32 v[90:91], v[38:39], v[68:69], v[34:35] op_sel_hi:[1,0,1] neg_lo:[0,0,1] neg_hi:[0,0,1]
	v_pk_mul_f32 v[34:35], v[150:151], v[94:95]
	v_pk_mul_f32 v[154:155], v[90:91], v[90:91]
	v_pk_fma_f32 v[80:81], v[44:45], v[68:69], v[34:35] op_sel_hi:[1,0,1] neg_lo:[0,0,1] neg_hi:[0,0,1]
	v_add_f32_e32 v0, v154, v0
	v_pk_mul_f32 v[34:35], v[150:151], v[92:93]
	v_add_f32_e32 v0, v155, v0
	v_pk_fma_f32 v[92:93], v[42:43], v[68:69], v[34:35] op_sel_hi:[1,0,1] neg_lo:[0,0,1] neg_hi:[0,0,1]
	v_add_f32_e32 v0, v148, v0
	v_pk_mul_f32 v[156:157], v[92:93], v[92:93]
	v_add_f32_e32 v0, v149, v0
	v_pk_mul_f32 v[34:35], v[150:151], v[98:99]
	v_add_f32_e32 v0, v156, v0
	v_pk_mul_f32 v[94:95], v[80:81], v[80:81]
	v_pk_fma_f32 v[74:75], v[48:49], v[68:69], v[34:35] op_sel_hi:[1,0,1] neg_lo:[0,0,1] neg_hi:[0,0,1]
	v_pk_mul_f32 v[34:35], v[150:151], v[96:97]
	v_add_f32_e32 v0, v157, v0
	v_pk_fma_f32 v[84:85], v[46:47], v[68:69], v[34:35] op_sel_hi:[1,0,1] neg_lo:[0,0,1] neg_hi:[0,0,1]
	v_add_f32_e32 v0, v94, v0
	v_pk_mul_f32 v[96:97], v[84:85], v[84:85]
	v_add_f32_e32 v0, v95, v0
	v_pk_mul_f32 v[34:35], v[150:151], v[102:103]
	v_add_f32_e32 v0, v96, v0
	v_pk_mul_f32 v[98:99], v[74:75], v[74:75]
	v_pk_fma_f32 v[52:53], v[52:53], v[68:69], v[34:35] op_sel_hi:[1,0,1] neg_lo:[0,0,1] neg_hi:[0,0,1]
	v_pk_mul_f32 v[34:35], v[150:151], v[100:101]
	v_add_f32_e32 v0, v97, v0
	v_pk_fma_f32 v[76:77], v[50:51], v[68:69], v[34:35] op_sel_hi:[1,0,1] neg_lo:[0,0,1] neg_hi:[0,0,1]
	v_add_f32_e32 v0, v98, v0
	v_pk_mul_f32 v[100:101], v[76:77], v[76:77]
	v_add_f32_e32 v0, v99, v0
	v_pk_mul_f32 v[34:35], v[150:151], v[106:107]
	v_add_f32_e32 v0, v100, v0
	v_pk_mul_f32 v[102:103], v[52:53], v[52:53]
	v_pk_fma_f32 v[46:47], v[56:57], v[68:69], v[34:35] op_sel_hi:[1,0,1] neg_lo:[0,0,1] neg_hi:[0,0,1]
	v_pk_mul_f32 v[34:35], v[150:151], v[104:105]
	v_add_f32_e32 v0, v101, v0
	v_pk_fma_f32 v[54:55], v[54:55], v[68:69], v[34:35] op_sel_hi:[1,0,1] neg_lo:[0,0,1] neg_hi:[0,0,1]
	v_add_f32_e32 v0, v102, v0
	v_pk_mul_f32 v[104:105], v[54:55], v[54:55]
	v_add_f32_e32 v0, v103, v0
	v_pk_mul_f32 v[34:35], v[150:151], v[110:111]
	v_add_f32_e32 v0, v104, v0
	v_pk_mul_f32 v[56:57], v[46:47], v[46:47]
	v_pk_fma_f32 v[44:45], v[60:61], v[68:69], v[34:35] op_sel_hi:[1,0,1] neg_lo:[0,0,1] neg_hi:[0,0,1]
	v_pk_mul_f32 v[34:35], v[150:151], v[108:109]
	v_add_f32_e32 v0, v105, v0
	v_pk_fma_f32 v[50:51], v[58:59], v[68:69], v[34:35] op_sel_hi:[1,0,1] neg_lo:[0,0,1] neg_hi:[0,0,1]
	v_add_f32_e32 v0, v56, v0
	v_pk_mul_f32 v[58:59], v[50:51], v[50:51]
	v_add_f32_e32 v0, v57, v0
	v_pk_mul_f32 v[34:35], v[150:151], v[114:115]
	v_add_f32_e32 v0, v58, v0
	v_pk_mul_f32 v[60:61], v[44:45], v[44:45]
	v_pk_fma_f32 v[40:41], v[64:65], v[68:69], v[34:35] op_sel_hi:[1,0,1] neg_lo:[0,0,1] neg_hi:[0,0,1]
	v_pk_mul_f32 v[34:35], v[150:151], v[112:113]
	v_add_f32_e32 v0, v59, v0
	v_pk_fma_f32 v[48:49], v[62:63], v[68:69], v[34:35] op_sel_hi:[1,0,1] neg_lo:[0,0,1] neg_hi:[0,0,1]
	v_add_f32_e32 v0, v60, v0
	v_pk_mul_f32 v[62:63], v[48:49], v[48:49]
	v_add_f32_e32 v0, v61, v0
	v_pk_mul_f32 v[34:35], v[150:151], v[118:119]
	v_add_f32_e32 v0, v62, v0
	v_pk_mul_f32 v[64:65], v[40:41], v[40:41]
	v_pk_fma_f32 v[36:37], v[20:21], v[68:69], v[34:35] op_sel_hi:[1,0,1] neg_lo:[0,0,1] neg_hi:[0,0,1]
	v_pk_mul_f32 v[20:21], v[150:151], v[116:117]
	v_add_f32_e32 v0, v63, v0
	v_pk_fma_f32 v[42:43], v[18:19], v[68:69], v[20:21] op_sel_hi:[1,0,1] neg_lo:[0,0,1] neg_hi:[0,0,1]
	v_add_f32_e32 v0, v64, v0
	v_pk_mul_f32 v[108:109], v[42:43], v[42:43]
	v_add_f32_e32 v0, v65, v0
	v_pk_mul_f32 v[18:19], v[150:151], v[122:123]
	v_add_f32_e32 v0, v108, v0
	v_pk_mul_f32 v[106:107], v[36:37], v[36:37]
	v_pk_fma_f32 v[34:35], v[24:25], v[68:69], v[18:19] op_sel_hi:[1,0,1] neg_lo:[0,0,1] neg_hi:[0,0,1]
	v_pk_mul_f32 v[18:19], v[150:151], v[120:121]
	v_add_f32_e32 v0, v109, v0
	v_pk_fma_f32 v[38:39], v[22:23], v[68:69], v[18:19] op_sel_hi:[1,0,1] neg_lo:[0,0,1] neg_hi:[0,0,1]
	v_add_f32_e32 v0, v106, v0
	v_pk_mul_f32 v[112:113], v[38:39], v[38:39]
	v_add_f32_e32 v0, v107, v0
	v_pk_mul_f32 v[18:19], v[150:151], v[126:127]
	v_add_f32_e32 v0, v112, v0
	v_pk_mul_f32 v[110:111], v[34:35], v[34:35]
	v_pk_fma_f32 v[24:25], v[28:29], v[68:69], v[18:19] op_sel_hi:[1,0,1] neg_lo:[0,0,1] neg_hi:[0,0,1]
	v_pk_mul_f32 v[18:19], v[150:151], v[124:125]
	v_add_f32_e32 v0, v113, v0
	v_pk_fma_f32 v[28:29], v[26:27], v[68:69], v[18:19] op_sel_hi:[1,0,1] neg_lo:[0,0,1] neg_hi:[0,0,1]
	v_add_f32_e32 v0, v110, v0
	v_pk_mul_f32 v[116:117], v[28:29], v[28:29]
	v_add_f32_e32 v0, v111, v0
	v_pk_mul_f32 v[18:19], v[150:151], v[130:131]
	v_add_f32_e32 v0, v116, v0
	v_pk_mul_f32 v[114:115], v[24:25], v[24:25]
	v_pk_fma_f32 v[20:21], v[32:33], v[68:69], v[18:19] op_sel_hi:[1,0,1] neg_lo:[0,0,1] neg_hi:[0,0,1]
	v_pk_mul_f32 v[18:19], v[150:151], v[128:129]
	v_add_f32_e32 v0, v117, v0
	v_pk_fma_f32 v[26:27], v[30:31], v[68:69], v[18:19] op_sel_hi:[1,0,1] neg_lo:[0,0,1] neg_hi:[0,0,1]
	v_add_f32_e32 v0, v114, v0
	v_pk_mul_f32 v[30:31], v[26:27], v[26:27]
	v_add_f32_e32 v0, v115, v0
	v_pk_mul_f32 v[18:19], v[150:151], v[134:135]
	v_add_f32_e32 v0, v30, v0
	v_pk_mul_f32 v[32:33], v[20:21], v[20:21]
	v_pk_fma_f32 v[18:19], v[4:5], v[68:69], v[18:19] op_sel_hi:[1,0,1] neg_lo:[0,0,1] neg_hi:[0,0,1]
	v_pk_mul_f32 v[4:5], v[150:151], v[132:133]
	v_add_f32_e32 v0, v31, v0
	v_pk_fma_f32 v[22:23], v[2:3], v[68:69], v[4:5] op_sel_hi:[1,0,1] neg_lo:[0,0,1] neg_hi:[0,0,1]
	v_add_f32_e32 v0, v32, v0
	v_pk_mul_f32 v[120:121], v[22:23], v[22:23]
	v_add_f32_e32 v0, v33, v0
	v_pk_mul_f32 v[2:3], v[150:151], v[138:139]
	v_add_f32_e32 v0, v120, v0
	v_pk_mul_f32 v[118:119], v[18:19], v[18:19]
	v_pk_fma_f32 v[4:5], v[8:9], v[68:69], v[2:3] op_sel_hi:[1,0,1] neg_lo:[0,0,1] neg_hi:[0,0,1]
	v_pk_mul_f32 v[2:3], v[150:151], v[136:137]
	v_add_f32_e32 v0, v121, v0
	v_pk_fma_f32 v[8:9], v[6:7], v[68:69], v[2:3] op_sel_hi:[1,0,1] neg_lo:[0,0,1] neg_hi:[0,0,1]
	v_add_f32_e32 v0, v118, v0
	v_pk_mul_f32 v[124:125], v[8:9], v[8:9]
	v_add_f32_e32 v0, v119, v0
	v_add_f32_e32 v0, v124, v0
	v_pk_mul_f32 v[122:123], v[4:5], v[4:5]
	v_pk_mul_f32 v[6:7], v[150:151], v[140:141]
	v_add_f32_e32 v0, v125, v0
	v_pk_fma_f32 v[6:7], v[10:11], v[68:69], v[6:7] op_sel_hi:[1,0,1] neg_lo:[0,0,1] neg_hi:[0,0,1]
	v_add_f32_e32 v0, v122, v0
	v_pk_mul_f32 v[2:3], v[150:151], v[142:143]
	v_pk_mul_f32 v[10:11], v[6:7], v[6:7]
	v_add_f32_e32 v0, v123, v0
	v_pk_fma_f32 v[2:3], v[12:13], v[68:69], v[2:3] op_sel_hi:[1,0,1] neg_lo:[0,0,1] neg_hi:[0,0,1]
	v_add_f32_e32 v0, v10, v0
	v_pk_mul_f32 v[12:13], v[2:3], v[2:3]
	v_add_f32_e32 v0, v11, v0
	v_add_f32_e32 v0, v12, v0
	v_add_f32_e32 v0, v13, v0
	v_add_f32_e32 v0, v72, v0
	v_add_f32_e32 v0, v73, v0
	v_add_f32_e32 v0, v78, v0
	v_add_f32_e32 v0, v79, v0
	ds_bpermute_b32 v10, v164, v0
	s_waitcnt lgkmcnt(0)
	v_add_f32_e32 v0, v0, v10
	v_fmamk_f32 v0, v0, 0x3c000000, v244
	v_cmp_gt_f32_e32 vcc, s33, v0
	v_mul_f32_e32 v10, 0x4b800000, v0
	s_nop 0
	v_cndmask_b32_e32 v0, v0, v10, vcc
	v_rsq_f32_e32 v0, v0
	s_nop 0
	v_mul_f32_e32 v10, 0x45800000, v0
	v_cndmask_b32_e32 v0, v0, v10, vcc
	v_mul_f32_e32 v0, v166, v0
	v_pk_mul_f32 v[10:11], v[86:87], v[0:1] op_sel_hi:[1,0]
	v_pk_mul_f32 v[12:13], v[88:89], v[0:1] op_sel_hi:[1,0]
	v_cvt_pk_bf16_f32 v10, v10, v11
	v_cvt_pk_bf16_f32 v11, v12, v13
	v_add_co_u32_e32 v12, vcc, s0, v70
	s_nop 1
	v_addc_co_u32_e32 v13, vcc, 0, v71, vcc
	global_store_dwordx2 v[12:13], v[10:11], off offset:1024
	s_nop 1
	v_pk_mul_f32 v[10:11], v[90:91], v[158:159]
	v_pk_mul_f32 v[12:13], v[82:83], v[160:161]
	v_pk_mul_f32 v[10:11], v[10:11], v[0:1] op_sel_hi:[1,0]
	v_pk_mul_f32 v[12:13], v[12:13], v[0:1] op_sel_hi:[1,0]
	v_cvt_pk_bf16_f32 v10, v10, v11
	v_cvt_pk_bf16_f32 v11, v12, v13
	global_store_dwordx2 v[66:67], v[10:11], off offset:16
	s_nop 1
	v_pk_mul_f32 v[10:11], v[92:93], v[170:171]
	v_pk_mul_f32 v[12:13], v[80:81], v[172:173]
	v_pk_mul_f32 v[10:11], v[10:11], v[0:1] op_sel_hi:[1,0]
	v_pk_mul_f32 v[12:13], v[12:13], v[0:1] op_sel_hi:[1,0]
	v_cvt_pk_bf16_f32 v10, v10, v11
	v_cvt_pk_bf16_f32 v11, v12, v13
	global_store_dwordx2 v[66:67], v[10:11], off offset:32
	s_nop 1
	v_pk_mul_f32 v[10:11], v[84:85], v[174:175]
	v_pk_mul_f32 v[12:13], v[74:75], v[176:177]
	v_pk_mul_f32 v[10:11], v[10:11], v[0:1] op_sel_hi:[1,0]
	v_pk_mul_f32 v[12:13], v[12:13], v[0:1] op_sel_hi:[1,0]
	v_cvt_pk_bf16_f32 v10, v10, v11
	v_cvt_pk_bf16_f32 v11, v12, v13
	global_store_dwordx2 v[66:67], v[10:11], off offset:48
	s_nop 1
	v_pk_mul_f32 v[10:11], v[76:77], v[178:179]
	v_pk_mul_f32 v[12:13], v[52:53], v[180:181]
	v_pk_mul_f32 v[10:11], v[10:11], v[0:1] op_sel_hi:[1,0]
	v_pk_mul_f32 v[12:13], v[12:13], v[0:1] op_sel_hi:[1,0]
	v_cvt_pk_bf16_f32 v10, v10, v11
	v_cvt_pk_bf16_f32 v11, v12, v13
	global_store_dwordx2 v[66:67], v[10:11], off offset:64
	s_nop 1
	v_pk_mul_f32 v[10:11], v[54:55], v[182:183]
	v_pk_mul_f32 v[12:13], v[46:47], v[184:185]
	v_pk_mul_f32 v[10:11], v[10:11], v[0:1] op_sel_hi:[1,0]
	v_pk_mul_f32 v[12:13], v[12:13], v[0:1] op_sel_hi:[1,0]
	v_cvt_pk_bf16_f32 v10, v10, v11
	v_cvt_pk_bf16_f32 v11, v12, v13
	global_store_dwordx2 v[66:67], v[10:11], off offset:80
	s_nop 1
	v_pk_mul_f32 v[10:11], v[50:51], v[186:187]
	v_pk_mul_f32 v[12:13], v[44:45], v[188:189]
	v_pk_mul_f32 v[10:11], v[10:11], v[0:1] op_sel_hi:[1,0]
	v_pk_mul_f32 v[12:13], v[12:13], v[0:1] op_sel_hi:[1,0]
	v_cvt_pk_bf16_f32 v10, v10, v11
	v_cvt_pk_bf16_f32 v11, v12, v13
	global_store_dwordx2 v[66:67], v[10:11], off offset:96
	s_nop 1
	v_pk_mul_f32 v[10:11], v[48:49], v[190:191]
	v_pk_mul_f32 v[12:13], v[40:41], v[192:193]
	v_pk_mul_f32 v[10:11], v[10:11], v[0:1] op_sel_hi:[1,0]
	v_pk_mul_f32 v[12:13], v[12:13], v[0:1] op_sel_hi:[1,0]
	v_cvt_pk_bf16_f32 v10, v10, v11
	v_cvt_pk_bf16_f32 v11, v12, v13
	global_store_dwordx2 v[66:67], v[10:11], off offset:112
	s_nop 1
	v_pk_mul_f32 v[10:11], v[42:43], v[194:195]
	v_pk_mul_f32 v[12:13], v[36:37], v[196:197]
	v_pk_mul_f32 v[10:11], v[10:11], v[0:1] op_sel_hi:[1,0]
	v_pk_mul_f32 v[12:13], v[12:13], v[0:1] op_sel_hi:[1,0]
	v_cvt_pk_bf16_f32 v10, v10, v11
	v_cvt_pk_bf16_f32 v11, v12, v13
	global_store_dwordx2 v[66:67], v[10:11], off offset:128
	s_nop 1
	v_pk_mul_f32 v[10:11], v[38:39], v[198:199]
	v_pk_mul_f32 v[12:13], v[34:35], v[200:201]
	v_pk_mul_f32 v[10:11], v[10:11], v[0:1] op_sel_hi:[1,0]
	v_pk_mul_f32 v[12:13], v[12:13], v[0:1] op_sel_hi:[1,0]
	v_cvt_pk_bf16_f32 v10, v10, v11
	v_cvt_pk_bf16_f32 v11, v12, v13
	global_store_dwordx2 v[66:67], v[10:11], off offset:144
	s_nop 1
	v_pk_mul_f32 v[10:11], v[28:29], v[202:203]
	v_pk_mul_f32 v[12:13], v[24:25], v[204:205]
	v_pk_mul_f32 v[10:11], v[10:11], v[0:1] op_sel_hi:[1,0]
	v_pk_mul_f32 v[12:13], v[12:13], v[0:1] op_sel_hi:[1,0]
	v_cvt_pk_bf16_f32 v10, v10, v11
	v_cvt_pk_bf16_f32 v11, v12, v13
	global_store_dwordx2 v[66:67], v[10:11], off offset:160
	s_nop 1
	v_pk_mul_f32 v[10:11], v[26:27], v[206:207]
	v_pk_mul_f32 v[12:13], v[20:21], v[208:209]
	v_pk_mul_f32 v[10:11], v[10:11], v[0:1] op_sel_hi:[1,0]
	v_pk_mul_f32 v[12:13], v[12:13], v[0:1] op_sel_hi:[1,0]
	v_cvt_pk_bf16_f32 v10, v10, v11
	v_cvt_pk_bf16_f32 v11, v12, v13
	global_store_dwordx2 v[66:67], v[10:11], off offset:176
	s_nop 1
	v_pk_mul_f32 v[10:11], v[22:23], v[210:211]
	v_pk_mul_f32 v[12:13], v[18:19], v[212:213]
	v_pk_mul_f32 v[10:11], v[10:11], v[0:1] op_sel_hi:[1,0]
	v_pk_mul_f32 v[12:13], v[12:13], v[0:1] op_sel_hi:[1,0]
	v_cvt_pk_bf16_f32 v10, v10, v11
	v_cvt_pk_bf16_f32 v11, v12, v13
	global_store_dwordx2 v[66:67], v[10:11], off offset:192
	s_nop 1
	v_pk_mul_f32 v[8:9], v[8:9], v[214:215]
	v_pk_mul_f32 v[4:5], v[4:5], v[216:217]
	v_pk_mul_f32 v[8:9], v[8:9], v[0:1] op_sel_hi:[1,0]
	v_pk_mul_f32 v[4:5], v[4:5], v[0:1] op_sel_hi:[1,0]
	v_cvt_pk_bf16_f32 v8, v8, v9
	v_cvt_pk_bf16_f32 v9, v4, v5
	global_store_dwordx2 v[66:67], v[8:9], off offset:208
	s_nop 1
	v_pk_mul_f32 v[4:5], v[6:7], v[218:219]
	v_pk_mul_f32 v[2:3], v[2:3], v[220:221]
	v_pk_mul_f32 v[4:5], v[4:5], v[0:1] op_sel_hi:[1,0]
	v_pk_mul_f32 v[2:3], v[2:3], v[0:1] op_sel_hi:[1,0]
	v_cvt_pk_bf16_f32 v4, v4, v5
	v_cvt_pk_bf16_f32 v5, v2, v3
	global_store_dwordx2 v[66:67], v[4:5], off offset:224
	s_nop 1
	v_pk_mul_f32 v[2:3], v[14:15], v[222:223]
	v_pk_mul_f32 v[4:5], v[16:17], v[224:225]
	v_pk_mul_f32 v[2:3], v[2:3], v[0:1] op_sel_hi:[1,0]
	v_pk_mul_f32 v[4:5], v[4:5], v[0:1] op_sel_hi:[1,0]
	v_cvt_pk_bf16_f32 v2, v2, v3
	v_cvt_pk_bf16_f32 v3, v4, v5
	global_store_dwordx2 v[66:67], v[2:3], off offset:240
	s_branch .LBB0_101
